# same as previous plus s_nop wait states between VALU accumulator init and first QK MFMA (hazard fix)
# baseline (speedup 1.0000x reference)
.LBB0_824:
	s_add_i32 s12, s13, 2
	s_min_i32 s4, s12, s10
	v_mad_u64_u32 v[34:35], s[4:5], s4, v231, v[98:99]
	global_load_dwordx4 v[90:93], v[34:35], off offset:768
	global_load_dwordx4 v[94:97], v[34:35], off offset:1536
	s_cmp_gt_i32 s13, s9
	s_cbranch_scc1 .LBB0_832
	ds_read_b128 v[34:37], v110
	ds_read_b128 v[38:41], v110 offset:32
	ds_read_b128 v[42:45], v110 offset:64
	ds_read_b128 v[46:49], v110 offset:96
	ds_read_b128 v[116:119], v113
	ds_read_b128 v[120:123], v113 offset:32
	ds_read_b128 v[124:127], v113 offset:64
	ds_read_b128 v[182:185], v113 offset:96
	ds_read_b128 v[50:53], v110 offset:128
	ds_read_b128 v[54:57], v110 offset:160
	ds_read_b128 v[58:61], v110 offset:192
	ds_read_b128 v[62:65], v110 offset:224
	ds_read_b128 v[186:189], v113 offset:4608
	ds_read_b128 v[190:193], v113 offset:4640
	ds_read_b128 v[242:245], v113 offset:4672
	ds_read_b128 v[246:249], v113 offset:4704
	v_sub_f32_e32 v1, v105, v112
	s_waitcnt lgkmcnt(12)
	v_sub_f32_e32 v34, v1, v34
	v_sub_f32_e32 v35, v1, v35
	v_sub_f32_e32 v36, v1, v36
	v_sub_f32_e32 v37, v1, v37
	v_sub_f32_e32 v38, v1, v38
	v_sub_f32_e32 v39, v1, v39
	v_sub_f32_e32 v40, v1, v40
	v_sub_f32_e32 v41, v1, v41
	v_sub_f32_e32 v42, v1, v42
	v_sub_f32_e32 v43, v1, v43
	v_sub_f32_e32 v44, v1, v44
	v_sub_f32_e32 v45, v1, v45
	v_sub_f32_e32 v46, v1, v46
	v_sub_f32_e32 v47, v1, v47
	v_sub_f32_e32 v48, v1, v48
	v_sub_f32_e32 v49, v1, v49
	s_waitcnt vmcnt(4) lgkmcnt(4)
	s_nop 0
	v_mfma_f32_32x32x16_bf16 v[34:49], v[116:119], v[66:69], v[34:49]
	v_sub_f32_e32 v50, v1, v50
	v_sub_f32_e32 v51, v1, v51
	v_sub_f32_e32 v52, v1, v52
	v_sub_f32_e32 v53, v1, v53
	s_waitcnt lgkmcnt(4)
	v_mfma_f32_32x32x16_bf16 v[34:49], v[120:123], v[70:73], v[34:49]
	v_sub_f32_e32 v54, v1, v54
	v_sub_f32_e32 v55, v1, v55
	v_sub_f32_e32 v56, v1, v56
	v_sub_f32_e32 v57, v1, v57
	s_waitcnt lgkmcnt(4)
	v_mfma_f32_32x32x16_bf16 v[34:49], v[124:127], v[74:77], v[34:49]
	v_sub_f32_e32 v58, v1, v58
	v_sub_f32_e32 v59, v1, v59
	v_sub_f32_e32 v60, v1, v60
	v_sub_f32_e32 v61, v1, v61
	s_waitcnt lgkmcnt(0)
	v_mfma_f32_32x32x16_bf16 v[34:49], v[182:185], v[78:81], v[34:49]
	v_sub_f32_e32 v62, v1, v62
	v_sub_f32_e32 v63, v1, v63
	v_sub_f32_e32 v64, v1, v64
	v_sub_f32_e32 v65, v1, v65
	s_nop 1
	v_mfma_f32_32x32x16_bf16 v[50:65], v[186:189], v[66:69], v[50:65]
	ds_read_b64_tr_b16 v[198:199], v108 offset:9216
	ds_read_b64_tr_b16 v[200:201], v108 offset:10368
	ds_read_b64_tr_b16 v[202:203], v108 offset:11520
	ds_read_b64_tr_b16 v[204:205], v108 offset:12672
	v_mfma_f32_32x32x16_bf16 v[50:65], v[190:193], v[70:73], v[50:65]
	ds_read_b64_tr_b16 v[206:207], v108 offset:13824
	ds_read_b64_tr_b16 v[208:209], v108 offset:14976
	ds_read_b64_tr_b16 v[210:211], v108 offset:16128
	ds_read_b64_tr_b16 v[212:213], v108 offset:17280
	v_mfma_f32_32x32x16_bf16 v[50:65], v[242:245], v[74:77], v[50:65]
	ds_read_b64_tr_b16 v[214:215], v108 offset:9280
	ds_read_b64_tr_b16 v[216:217], v108 offset:10432
	ds_read_b64_tr_b16 v[218:219], v108 offset:11584
	ds_read_b64_tr_b16 v[220:221], v108 offset:12736
	v_mfma_f32_32x32x16_bf16 v[50:65], v[246:249], v[78:81], v[50:65]
	ds_read_b64_tr_b16 v[234:235], v108 offset:13888
	ds_read_b64_tr_b16 v[236:237], v108 offset:15040
	ds_read_b64_tr_b16 v[238:239], v108 offset:16192
	ds_read_b64_tr_b16 v[240:241], v108 offset:17344
	s_nop 1
	s_cmp_lg_u32 s9, s13
	s_cbranch_scc1 .LBB0_827
	v_add_u32_e32 v104, 0xffffffa5, v111
	v_add_u32_e32 v1, 0xffffff85, v111
	v_cmp_le_i32_e32 vcc, v104, v102
	s_nop 7
	v_cndmask_b32_e32 v50, v232, v50, vcc
	v_cmp_lt_i32_e32 vcc, v1, v102
	s_nop 1
	v_cndmask_b32_e32 v35, v232, v35, vcc
	v_cmp_le_i32_e32 vcc, v1, v102
	v_add_u32_e32 v1, 0xffffffa6, v111
	s_nop 0
	v_cndmask_b32_e32 v34, v232, v34, vcc
	v_cmp_le_i32_e32 vcc, v1, v102
	v_add_u32_e32 v1, 0xffffff87, v111
	s_nop 0
	v_cndmask_b32_e32 v51, v232, v51, vcc
	v_cmp_le_i32_e32 vcc, v1, v102
	v_add_u32_e32 v1, 0xffffffa7, v111
	s_nop 0
	v_cndmask_b32_e32 v36, v232, v36, vcc
	v_cmp_le_i32_e32 vcc, v1, v102
	v_add_u32_e32 v1, 0xffffff88, v111
	s_nop 0
	v_cndmask_b32_e32 v52, v232, v52, vcc
	v_cmp_le_i32_e32 vcc, v1, v102
	v_add_u32_e32 v1, 0xffffffa8, v111
	s_nop 0
	v_cndmask_b32_e32 v37, v232, v37, vcc
	v_cmp_le_i32_e32 vcc, v1, v102
	v_add_u32_e32 v1, 0xffffff8d, v111
	s_nop 0
	v_cndmask_b32_e32 v53, v232, v53, vcc
	v_cmp_le_i32_e32 vcc, v1, v102
	v_add_u32_e32 v1, 0xffffffad, v111
	s_nop 0
	v_cndmask_b32_e32 v38, v232, v38, vcc
	v_cmp_le_i32_e32 vcc, v1, v102
	v_add_u32_e32 v1, 0xffffff8e, v111
	s_nop 0
	v_cndmask_b32_e32 v54, v232, v54, vcc
	v_cmp_le_i32_e32 vcc, v1, v102
	v_add_u32_e32 v1, 0xffffffae, v111
	s_nop 0
	v_cndmask_b32_e32 v39, v232, v39, vcc
	v_cmp_le_i32_e32 vcc, v1, v102
	v_add_u32_e32 v1, 0xffffff8f, v111
	s_nop 0
	v_cndmask_b32_e32 v55, v232, v55, vcc
	v_cmp_le_i32_e32 vcc, v1, v102
	v_add_u32_e32 v1, 0xffffffaf, v111
	s_nop 0
	v_cndmask_b32_e32 v40, v232, v40, vcc
	v_cmp_le_i32_e32 vcc, v1, v102
	v_add_u32_e32 v1, 0xffffff90, v111
	s_nop 0
	v_cndmask_b32_e32 v56, v232, v56, vcc
	v_cmp_le_i32_e32 vcc, v1, v102
	v_add_u32_e32 v1, 0xffffffb0, v111
	s_nop 0
	v_cndmask_b32_e32 v41, v232, v41, vcc
	v_cmp_le_i32_e32 vcc, v1, v102
	v_add_u32_e32 v1, 0xffffff95, v111
	s_nop 0
	v_cndmask_b32_e32 v57, v232, v57, vcc
	v_cmp_le_i32_e32 vcc, v1, v102
	v_add_u32_e32 v1, 0xffffffb5, v111
	s_nop 0
	v_cndmask_b32_e32 v42, v232, v42, vcc
	v_cmp_le_i32_e32 vcc, v1, v102
	v_add_u32_e32 v1, 0xffffff96, v111
	s_nop 0
	v_cndmask_b32_e32 v58, v232, v58, vcc
	v_cmp_le_i32_e32 vcc, v1, v102
	v_add_u32_e32 v1, 0xffffffb6, v111
	s_nop 0
	v_cndmask_b32_e32 v43, v232, v43, vcc
	v_cmp_le_i32_e32 vcc, v1, v102
	v_add_u32_e32 v1, 0xffffff97, v111
	s_nop 0
	v_cndmask_b32_e32 v59, v232, v59, vcc
	v_cmp_le_i32_e32 vcc, v1, v102
	v_add_u32_e32 v1, 0xffffffb7, v111
	s_nop 0
	v_cndmask_b32_e32 v44, v232, v44, vcc
	v_cmp_le_i32_e32 vcc, v1, v102
	v_add_u32_e32 v1, 0xffffff98, v111
	s_nop 0
	v_cndmask_b32_e32 v60, v232, v60, vcc
	v_cmp_le_i32_e32 vcc, v1, v102
	v_add_u32_e32 v1, 0xffffffb8, v111
	s_nop 0
	v_cndmask_b32_e32 v45, v232, v45, vcc
	v_cmp_le_i32_e32 vcc, v1, v102
	v_add_u32_e32 v1, 0xffffff9d, v111
	s_nop 0
	v_cndmask_b32_e32 v61, v232, v61, vcc
	v_cmp_le_i32_e32 vcc, v1, v102
	v_add_u32_e32 v1, 0xffffffbd, v111
	s_nop 0
	v_cndmask_b32_e32 v46, v232, v46, vcc
	v_cmp_le_i32_e32 vcc, v1, v102
	v_add_u32_e32 v1, 0xffffff9e, v111
	s_nop 0
	v_cndmask_b32_e32 v62, v232, v62, vcc
	v_cmp_le_i32_e32 vcc, v1, v102
	v_add_u32_e32 v1, 0xffffffbe, v111
	s_nop 0
	v_cndmask_b32_e32 v47, v232, v47, vcc
	v_cmp_le_i32_e32 vcc, v1, v102
	v_add_u32_e32 v1, 0xffffff9f, v111
	s_nop 0
	v_cndmask_b32_e32 v63, v232, v63, vcc
	v_cmp_le_i32_e32 vcc, v1, v102
	v_add_u32_e32 v1, 0xffffffbf, v111
	s_nop 0
	v_cndmask_b32_e32 v48, v232, v48, vcc
	v_cmp_le_i32_e32 vcc, v1, v102
	v_add_u32_e32 v1, 0xffffffa0, v111
	s_nop 0
	v_cndmask_b32_e32 v64, v232, v64, vcc
	v_cmp_le_i32_e32 vcc, v1, v102
	v_subrev_u32_e32 v1, 64, v111
	s_nop 0
	v_cndmask_b32_e32 v49, v232, v49, vcc
	v_cmp_le_i32_e32 vcc, v1, v102
	s_nop 1
	v_cndmask_b32_e32 v65, v232, v65, vcc

; #define LAS __attribute__((address_space(3)))
; #define STAGE_TILE(bufi, KR, VR) do { LAS bf16_t* Ks_ = (LAS bf16_t*)(lds + (bufi) * 18432); LAS bf16_t* Vs_ = (LAS bf16_t*)(lds + (bufi) * 18432 + 9216); \
;         *(LAS u32x4*)(Ks_ + skr * 72 + sch * 8) = KR; *(LAS u32x4*)(Vs_ + skr * 72 + sch * 8) = VR; } while (0)
; #define LOAD_TILE(KR, VR, tl) do { KR = *(const GAS u32x4*)(kg + (size_t)(tl) * 64 * LDH); VR = *(const GAS u32x4*)(vg + (size_t)(tl) * 64 * LDH); } while (0)
; template <int MODE> ...
;     ...
;         STAGE_TILE(1, kB, vB);
;         __syncthreads();
;         if (MODE == 1) { const u32x4 fa = *(const LAS u32x4*)flags, fb = *(const LAS u32x4*)(flags + 4); if ((fa.x & fa.y & fa.z & fa.w & fb.x & fb.y & fb.z & fb.w) != 0u) break; }
;         LOAD_TILE(kB, vB, TILE_OF(min(it + 3, ntiles - 1)));
;         COMPUTE_TILE(TILE_OF(it + 1), 1);
.LBB0_832:
	s_add_i32 s4, s13, 3
	s_min_i32 s4, s4, s10
	v_mad_u64_u32 v[34:35], s[4:5], s4, v231, v[98:99]
	s_waitcnt vmcnt(3)
	ds_write_b128 v107, v[82:85] offset:18432
	s_waitcnt vmcnt(2)
	ds_write_b128 v107, v[86:89] offset:27648
	s_waitcnt lgkmcnt(0)
	s_barrier
	global_load_dwordx4 v[82:85], v[34:35], off offset:768
	global_load_dwordx4 v[86:89], v[34:35], off offset:1536
	s_cmp_ge_i32 s13, s9
	s_cbranch_scc1 .LBB0_840
	ds_read_b128 v[34:37], v110 offset:256
	ds_read_b128 v[38:41], v110 offset:288
	ds_read_b128 v[42:45], v110 offset:320
	ds_read_b128 v[46:49], v110 offset:352
	ds_read_b128 v[116:119], v113 offset:18432
	ds_read_b128 v[120:123], v113 offset:18464
	ds_read_b128 v[124:127], v113 offset:18496
	ds_read_b128 v[182:185], v113 offset:18528
	ds_read_b128 v[50:53], v110 offset:384
	ds_read_b128 v[54:57], v110 offset:416
	ds_read_b128 v[58:61], v110 offset:448
	ds_read_b128 v[62:65], v110 offset:480
	ds_read_b128 v[186:189], v113 offset:23040
	ds_read_b128 v[190:193], v113 offset:23072
	ds_read_b128 v[242:245], v113 offset:23104
	ds_read_b128 v[246:249], v113 offset:23136
	v_sub_f32_e32 v1, v105, v112
	s_waitcnt lgkmcnt(12)
	v_sub_f32_e32 v34, v1, v34
	v_sub_f32_e32 v35, v1, v35
	v_sub_f32_e32 v36, v1, v36
	v_sub_f32_e32 v37, v1, v37
	v_sub_f32_e32 v38, v1, v38
	v_sub_f32_e32 v39, v1, v39
	v_sub_f32_e32 v40, v1, v40
	v_sub_f32_e32 v41, v1, v41
	v_sub_f32_e32 v42, v1, v42
	v_sub_f32_e32 v43, v1, v43
	v_sub_f32_e32 v44, v1, v44
	v_sub_f32_e32 v45, v1, v45
	v_sub_f32_e32 v46, v1, v46
	v_sub_f32_e32 v47, v1, v47
	v_sub_f32_e32 v48, v1, v48
	v_sub_f32_e32 v49, v1, v49
	s_waitcnt lgkmcnt(4)
	s_nop 0
	v_mfma_f32_32x32x16_bf16 v[34:49], v[116:119], v[66:69], v[34:49]
	v_sub_f32_e32 v50, v1, v50
	v_sub_f32_e32 v51, v1, v51
	v_sub_f32_e32 v52, v1, v52
	v_sub_f32_e32 v53, v1, v53
	s_waitcnt lgkmcnt(4)
	v_mfma_f32_32x32x16_bf16 v[34:49], v[120:123], v[70:73], v[34:49]
	v_sub_f32_e32 v54, v1, v54
	v_sub_f32_e32 v55, v1, v55
	v_sub_f32_e32 v56, v1, v56
	v_sub_f32_e32 v57, v1, v57
	s_waitcnt lgkmcnt(4)
	v_mfma_f32_32x32x16_bf16 v[34:49], v[124:127], v[74:77], v[34:49]
	v_sub_f32_e32 v58, v1, v58
	v_sub_f32_e32 v59, v1, v59
	v_sub_f32_e32 v60, v1, v60
	v_sub_f32_e32 v61, v1, v61
	s_waitcnt lgkmcnt(0)
	v_mfma_f32_32x32x16_bf16 v[34:49], v[182:185], v[78:81], v[34:49]
	v_sub_f32_e32 v62, v1, v62
	v_sub_f32_e32 v63, v1, v63
	v_sub_f32_e32 v64, v1, v64
	v_sub_f32_e32 v65, v1, v65
	s_nop 1
	v_mfma_f32_32x32x16_bf16 v[50:65], v[186:189], v[66:69], v[50:65]
	ds_read_b64_tr_b16 v[198:199], v108 offset:27648
	ds_read_b64_tr_b16 v[200:201], v108 offset:28800
	ds_read_b64_tr_b16 v[202:203], v108 offset:29952
	ds_read_b64_tr_b16 v[204:205], v108 offset:31104
	v_mfma_f32_32x32x16_bf16 v[50:65], v[190:193], v[70:73], v[50:65]
	ds_read_b64_tr_b16 v[206:207], v108 offset:32256
	ds_read_b64_tr_b16 v[208:209], v108 offset:33408
	ds_read_b64_tr_b16 v[210:211], v108 offset:34560
	ds_read_b64_tr_b16 v[212:213], v108 offset:35712
	v_mfma_f32_32x32x16_bf16 v[50:65], v[242:245], v[74:77], v[50:65]
	ds_read_b64_tr_b16 v[214:215], v108 offset:27712
	ds_read_b64_tr_b16 v[216:217], v108 offset:28864
	ds_read_b64_tr_b16 v[218:219], v108 offset:30016
	ds_read_b64_tr_b16 v[220:221], v108 offset:31168
	v_mfma_f32_32x32x16_bf16 v[50:65], v[246:249], v[78:81], v[50:65]
	ds_read_b64_tr_b16 v[234:235], v108 offset:32320
	ds_read_b64_tr_b16 v[236:237], v108 offset:33472
	ds_read_b64_tr_b16 v[238:239], v108 offset:34624
	ds_read_b64_tr_b16 v[240:241], v108 offset:35776
	s_nop 1
	s_cmp_lg_u32 s11, s13
	s_cbranch_scc1 .LBB0_835
	v_subrev_u32_e32 v104, 27, v111
	v_subrev_u32_e32 v1, 59, v111
	v_cmp_le_i32_e32 vcc, v104, v102
	s_nop 7
	v_cndmask_b32_e32 v50, v232, v50, vcc
	v_cmp_lt_i32_e32 vcc, v1, v102
	s_nop 1
	v_cndmask_b32_e32 v35, v232, v35, vcc
	v_cmp_le_i32_e32 vcc, v1, v102
	v_subrev_u32_e32 v1, 26, v111
	s_nop 0
	v_cndmask_b32_e32 v34, v232, v34, vcc
	v_cmp_le_i32_e32 vcc, v1, v102
	v_subrev_u32_e32 v1, 57, v111
	s_nop 0
	v_cndmask_b32_e32 v51, v232, v51, vcc
	v_cmp_le_i32_e32 vcc, v1, v102
	v_subrev_u32_e32 v1, 25, v111
	s_nop 0
	v_cndmask_b32_e32 v36, v232, v36, vcc
	v_cmp_le_i32_e32 vcc, v1, v102
	v_subrev_u32_e32 v1, 56, v111
	s_nop 0
	v_cndmask_b32_e32 v52, v232, v52, vcc
	v_cmp_le_i32_e32 vcc, v1, v102
	v_subrev_u32_e32 v1, 24, v111
	s_nop 0
	v_cndmask_b32_e32 v37, v232, v37, vcc
	v_cmp_le_i32_e32 vcc, v1, v102
	v_subrev_u32_e32 v1, 51, v111
	s_nop 0
	v_cndmask_b32_e32 v53, v232, v53, vcc
	v_cmp_le_i32_e32 vcc, v1, v102
	v_subrev_u32_e32 v1, 19, v111
	s_nop 0
	v_cndmask_b32_e32 v38, v232, v38, vcc
	v_cmp_le_i32_e32 vcc, v1, v102
	v_subrev_u32_e32 v1, 50, v111
	s_nop 0
	v_cndmask_b32_e32 v54, v232, v54, vcc
	v_cmp_le_i32_e32 vcc, v1, v102
	v_subrev_u32_e32 v1, 18, v111
	s_nop 0
	v_cndmask_b32_e32 v39, v232, v39, vcc
	v_cmp_le_i32_e32 vcc, v1, v102
	v_subrev_u32_e32 v1, 49, v111
	s_nop 0
	v_cndmask_b32_e32 v55, v232, v55, vcc
	v_cmp_le_i32_e32 vcc, v1, v102
	v_subrev_u32_e32 v1, 17, v111
	s_nop 0
	v_cndmask_b32_e32 v40, v232, v40, vcc
	v_cmp_le_i32_e32 vcc, v1, v102
	v_subrev_u32_e32 v1, 48, v111
	s_nop 0
	v_cndmask_b32_e32 v56, v232, v56, vcc
	v_cmp_le_i32_e32 vcc, v1, v102
	v_add_u32_e32 v1, -16, v111
	s_nop 0
	v_cndmask_b32_e32 v41, v232, v41, vcc
	v_cmp_le_i32_e32 vcc, v1, v102
	v_subrev_u32_e32 v1, 43, v111
	s_nop 0
	v_cndmask_b32_e32 v57, v232, v57, vcc
	v_cmp_le_i32_e32 vcc, v1, v102
	v_add_u32_e32 v1, -11, v111
	s_nop 0
	v_cndmask_b32_e32 v42, v232, v42, vcc
	v_cmp_le_i32_e32 vcc, v1, v102
	v_subrev_u32_e32 v1, 42, v111
	s_nop 0
	v_cndmask_b32_e32 v58, v232, v58, vcc
	v_cmp_le_i32_e32 vcc, v1, v102
	v_add_u32_e32 v1, -10, v111
	s_nop 0
	v_cndmask_b32_e32 v43, v232, v43, vcc
	v_cmp_le_i32_e32 vcc, v1, v102
	v_subrev_u32_e32 v1, 41, v111
	s_nop 0
	v_cndmask_b32_e32 v59, v232, v59, vcc
	v_cmp_le_i32_e32 vcc, v1, v102
	v_add_u32_e32 v1, -9, v111
	s_nop 0
	v_cndmask_b32_e32 v44, v232, v44, vcc
	v_cmp_le_i32_e32 vcc, v1, v102
	v_subrev_u32_e32 v1, 40, v111
	s_nop 0
	v_cndmask_b32_e32 v60, v232, v60, vcc
	v_cmp_le_i32_e32 vcc, v1, v102
	v_add_u32_e32 v1, -8, v111
	s_nop 0
	v_cndmask_b32_e32 v45, v232, v45, vcc
	v_cmp_le_i32_e32 vcc, v1, v102
	v_subrev_u32_e32 v1, 35, v111
	s_nop 0
	v_cndmask_b32_e32 v61, v232, v61, vcc
	v_cmp_le_i32_e32 vcc, v1, v102
	v_add_u32_e32 v1, -3, v111
	s_nop 0
	v_cndmask_b32_e32 v46, v232, v46, vcc
	v_cmp_le_i32_e32 vcc, v1, v102
	v_subrev_u32_e32 v1, 34, v111
	s_nop 0
	v_cndmask_b32_e32 v62, v232, v62, vcc
	v_cmp_le_i32_e32 vcc, v1, v102
	v_add_u32_e32 v1, -2, v111
	s_nop 0
	v_cndmask_b32_e32 v47, v232, v47, vcc
	v_cmp_le_i32_e32 vcc, v1, v102
	v_subrev_u32_e32 v1, 33, v111
	s_nop 0
	v_cndmask_b32_e32 v63, v232, v63, vcc
	v_cmp_le_i32_e32 vcc, v1, v102
	v_add_u32_e32 v1, -1, v111
	s_nop 0
	v_cndmask_b32_e32 v48, v232, v48, vcc
	v_cmp_le_i32_e32 vcc, v1, v102
	v_subrev_u32_e32 v1, 32, v111
	s_nop 0
	v_cndmask_b32_e32 v64, v232, v64, vcc
	v_cmp_le_i32_e32 vcc, v1, v102
	s_nop 1
	v_cndmask_b32_e32 v49, v232, v49, vcc
	v_cmp_le_i32_e32 vcc, v111, v102
	s_nop 1
	v_cndmask_b32_e32 v65, v232, v65, vcc

; #define LOAD_TILE(KR, VR, tl) do { KR = *(const GAS u32x4*)(kg + (size_t)(tl) * 64 * LDH); VR = *(const GAS u32x4*)(vg + (size_t)(tl) * 64 * LDH); } while (0)
; template <int MODE> ...
;     ...
;         LOAD_TILE(kreg, vreg, TILE_OF(min(it + 2, ntiles - 1)));
;         COMPUTE_TILE(TILE_OF(it), 0);
.LBB0_920:
	s_add_i32 s19, s23, 2
	s_min_i32 s14, s19, s18
	v_mad_u64_u32 v[34:35], s[12:13], s14, v231, v[102:103]
	v_mad_u64_u32 v[36:37], s[12:13], s14, v231, v[104:105]
	global_load_dwordx4 v[90:93], v[34:35], off
	global_load_dwordx4 v[94:97], v[36:37], off
	s_cmp_gt_i32 s23, s17
	s_cbranch_scc1 .LBB0_926
	ds_read_b64 v[34:35], v109
	ds_read_b128 v[118:121], v113
	ds_read_b128 v[122:125], v113 offset:32
	ds_read_b128 v[126:129], v113 offset:64
	ds_read_b128 v[130:133], v113 offset:96
	ds_read_b128 v[182:185], v113 offset:4608
	ds_read_b128 v[186:189], v113 offset:4640
	ds_read_b128 v[190:193], v113 offset:4672
	ds_read_b128 v[242:245], v113 offset:4704
	v_sub_f32_e32 v1, 0, v112
	s_xor_b64 s[10:11], s[10:11], -1
	s_waitcnt lgkmcnt(8)
	v_lshrrev_b64 v[114:115], v100, v[34:35]
	v_lshrrev_b64 v[116:117], v106, v[34:35]
	v_bfe_i32 v34, v114, 0, 1
	v_bfe_i32 v35, v114, 1, 1
	v_bfe_i32 v36, v114, 2, 1
	v_bfe_i32 v37, v114, 3, 1
	v_bfe_i32 v38, v114, 8, 1
	v_bfe_i32 v39, v114, 9, 1
	v_bfe_i32 v40, v114, 10, 1
	v_bfe_i32 v41, v114, 11, 1
	v_bfe_i32 v42, v114, 16, 1
	v_bfe_i32 v43, v114, 17, 1
	v_bfe_i32 v44, v114, 18, 1
	v_bfe_i32 v45, v114, 19, 1
	v_bfe_i32 v46, v114, 24, 1
	v_bfe_i32 v47, v114, 25, 1
	v_bfe_i32 v48, v114, 26, 1
	v_bfe_i32 v49, v114, 27, 1
	v_bfi_b32 v34, v34, v1, v232
	v_bfi_b32 v35, v35, v1, v232
	v_bfi_b32 v36, v36, v1, v232
	v_bfi_b32 v37, v37, v1, v232
	v_bfi_b32 v38, v38, v1, v232
	v_bfi_b32 v39, v39, v1, v232
	v_bfi_b32 v40, v40, v1, v232
	v_bfi_b32 v41, v41, v1, v232
	v_bfi_b32 v42, v42, v1, v232
	v_bfi_b32 v43, v43, v1, v232
	v_bfi_b32 v44, v44, v1, v232
	v_bfi_b32 v45, v45, v1, v232
	v_bfi_b32 v46, v46, v1, v232
	v_bfi_b32 v47, v47, v1, v232
	v_bfi_b32 v48, v48, v1, v232
	v_bfi_b32 v49, v49, v1, v232
	s_waitcnt vmcnt(4) lgkmcnt(4)
	s_nop 0
	v_mfma_f32_32x32x16_bf16 v[34:49], v[118:121], v[74:77], v[34:49]
	v_bfe_i32 v50, v116, 0, 1
	v_bfe_i32 v51, v116, 1, 1
	v_bfe_i32 v52, v116, 2, 1
	v_bfe_i32 v53, v116, 3, 1
	v_bfe_i32 v54, v116, 8, 1
	v_bfe_i32 v55, v116, 9, 1
	v_bfe_i32 v56, v116, 10, 1
	v_bfe_i32 v57, v116, 11, 1
	s_waitcnt lgkmcnt(4)
	v_mfma_f32_32x32x16_bf16 v[34:49], v[122:125], v[66:69], v[34:49]
	v_bfe_i32 v58, v116, 16, 1
	v_bfe_i32 v59, v116, 17, 1
	v_bfe_i32 v60, v116, 18, 1
	v_bfe_i32 v61, v116, 19, 1
	v_bfe_i32 v62, v116, 24, 1
	v_bfe_i32 v63, v116, 25, 1
	v_bfe_i32 v64, v116, 26, 1
	v_bfe_i32 v65, v116, 27, 1
	s_waitcnt lgkmcnt(4)
	v_mfma_f32_32x32x16_bf16 v[34:49], v[126:129], v[70:73], v[34:49]
	v_bfi_b32 v50, v50, v1, v232
	v_bfi_b32 v51, v51, v1, v232
	v_bfi_b32 v52, v52, v1, v232
	v_bfi_b32 v53, v53, v1, v232
	v_bfi_b32 v54, v54, v1, v232
	v_bfi_b32 v55, v55, v1, v232
	v_bfi_b32 v56, v56, v1, v232
	v_bfi_b32 v57, v57, v1, v232
	s_waitcnt lgkmcnt(0)
	v_mfma_f32_32x32x16_bf16 v[34:49], v[130:133], v[78:81], v[34:49]
	v_bfi_b32 v58, v58, v1, v232
	v_bfi_b32 v59, v59, v1, v232
	v_bfi_b32 v60, v60, v1, v232
	v_bfi_b32 v61, v61, v1, v232
	v_bfi_b32 v62, v62, v1, v232
	v_bfi_b32 v63, v63, v1, v232
	v_bfi_b32 v64, v64, v1, v232
	v_bfi_b32 v65, v65, v1, v232
	s_nop 1
	v_mfma_f32_32x32x16_bf16 v[50:65], v[182:185], v[74:77], v[50:65]
	ds_read_b64_tr_b16 v[198:199], v107 offset:9216
	ds_read_b64_tr_b16 v[200:201], v107 offset:10368
	ds_read_b64_tr_b16 v[202:203], v107 offset:11520
	ds_read_b64_tr_b16 v[204:205], v107 offset:12672
	v_mfma_f32_32x32x16_bf16 v[50:65], v[186:189], v[66:69], v[50:65]
	ds_read_b64_tr_b16 v[206:207], v107 offset:13824
	ds_read_b64_tr_b16 v[208:209], v107 offset:14976
	ds_read_b64_tr_b16 v[210:211], v107 offset:16128
	ds_read_b64_tr_b16 v[212:213], v107 offset:17280
	v_mfma_f32_32x32x16_bf16 v[50:65], v[190:193], v[70:73], v[50:65]
	ds_read_b64_tr_b16 v[214:215], v107 offset:9280
	ds_read_b64_tr_b16 v[216:217], v107 offset:10432
	ds_read_b64_tr_b16 v[218:219], v107 offset:11584
	ds_read_b64_tr_b16 v[220:221], v107 offset:12736
	v_mfma_f32_32x32x16_bf16 v[50:65], v[242:245], v[78:81], v[50:65]
	ds_read_b64_tr_b16 v[234:235], v107 offset:13888
	ds_read_b64_tr_b16 v[236:237], v107 offset:15040
	ds_read_b64_tr_b16 v[238:239], v107 offset:16192
	ds_read_b64_tr_b16 v[240:241], v107 offset:17344
	s_nop 1
	v_max3_f32 v108, v34, v35, v36
	v_max3_f32 v110, v37, v38, v39
	v_max3_f32 v114, v40, v41, v42
	v_max3_f32 v1, v43, v44, v45
	v_max3_f32 v108, v108, v46, v47
	v_max3_f32 v110, v110, v48, v49
	v_max3_f32 v114, v114, v50, v51
	v_max3_f32 v1, v1, v52, v53
	v_max3_f32 v108, v108, v54, v55
	v_max3_f32 v110, v110, v56, v57
	v_max3_f32 v114, v114, v58, v59
	v_max3_f32 v1, v1, v60, v61
	v_max3_f32 v108, v108, v62, v63
	v_max3_f32 v110, v110, v64, v65
	v_max3_f32 v1, v1, v114, s82
	v_max3_f32 v1, v1, v108, v110
	v_and_b32_e32 v110, 64, v224
	v_xor_b32_e32 v108, 32, v224
	v_add_u32_e32 v110, 64, v110
	v_cmp_lt_i32_e32 vcc, v108, v110
	s_nop 1
	v_cndmask_b32_e32 v108, v224, v108, vcc
	v_lshlrev_b32_e32 v108, 2, v108
	ds_bpermute_b32 v108, v108, v1
	s_waitcnt lgkmcnt(0)
	v_max_f32_e32 v108, v108, v108
	v_max_f32_e32 v1, v1, v108
	s_and_saveexec_b64 s[12:13], s[10:11]
	s_xor_b64 s[10:11], exec, s[12:13]
	s_cbranch_execnz .LBB0_934
	s_or_saveexec_b64 s[12:13], s[10:11]
	s_mov_b64 s[10:11], 0
	s_xor_b64 exec, exec, s[12:13]
	s_cbranch_execnz .LBB0_937

; #define LAS __attribute__((address_space(3)))
; #define STAGE_TILE(bufi, KR, VR) do { LAS bf16_t* Ks_ = (LAS bf16_t*)(lds + (bufi) * 18432); LAS bf16_t* Vs_ = (LAS bf16_t*)(lds + (bufi) * 18432 + 9216); \
;         *(LAS u32x4*)(Ks_ + skr * 72 + sch * 8) = KR; *(LAS u32x4*)(Vs_ + skr * 72 + sch * 8) = VR; } while (0)
; #define LOAD_TILE(KR, VR, tl) do { KR = *(const GAS u32x4*)(kg + (size_t)(tl) * 64 * LDH); VR = *(const GAS u32x4*)(vg + (size_t)(tl) * 64 * LDH); } while (0)
; template <int MODE> ...
;     ...
;         STAGE_TILE(1, kB, vB);
;         __syncthreads();
;         if (MODE == 1) { const u32x4 fa = *(const LAS u32x4*)flags, fb = *(const LAS u32x4*)(flags + 4); if ((fa.x & fa.y & fa.z & fa.w & fb.x & fb.y & fb.z & fb.w) != 0u) break; }
;         LOAD_TILE(kB, vB, TILE_OF(min(it + 3, ntiles - 1)));
;         COMPUTE_TILE(TILE_OF(it + 1), 1);
.LBB0_926:
	s_add_i32 s12, s23, 3
	s_min_i32 s14, s12, s18
	v_mad_u64_u32 v[34:35], s[12:13], s14, v231, v[102:103]
	s_waitcnt vmcnt(3)
	ds_write_b128 v101, v[82:85] offset:18432
	s_waitcnt vmcnt(2)
	ds_write_b128 v101, v[86:89] offset:27648
	s_waitcnt lgkmcnt(0)
	s_barrier
	v_mad_u64_u32 v[36:37], s[12:13], s14, v231, v[104:105]
	global_load_dwordx4 v[82:85], v[34:35], off
	global_load_dwordx4 v[86:89], v[36:37], off
	s_cmp_ge_i32 s23, s17
	s_cbranch_scc1 .LBB0_932
	ds_read_b64 v[34:35], v109 offset:8
	ds_read_b128 v[118:121], v113 offset:18432
	ds_read_b128 v[122:125], v113 offset:18464
	ds_read_b128 v[126:129], v113 offset:18496
	ds_read_b128 v[130:133], v113 offset:18528
	ds_read_b128 v[182:185], v113 offset:23040
	ds_read_b128 v[186:189], v113 offset:23072
	ds_read_b128 v[190:193], v113 offset:23104
	ds_read_b128 v[242:245], v113 offset:23136
	v_sub_f32_e32 v1, 0, v112
	s_xor_b64 s[10:11], s[10:11], -1
	s_waitcnt lgkmcnt(8)
	v_lshrrev_b64 v[114:115], v100, v[34:35]
	v_lshrrev_b64 v[116:117], v106, v[34:35]
	v_bfe_i32 v34, v114, 0, 1
	v_bfe_i32 v35, v114, 1, 1
	v_bfe_i32 v36, v114, 2, 1
	v_bfe_i32 v37, v114, 3, 1
	v_bfe_i32 v38, v114, 8, 1
	v_bfe_i32 v39, v114, 9, 1
	v_bfe_i32 v40, v114, 10, 1
	v_bfe_i32 v41, v114, 11, 1
	v_bfe_i32 v42, v114, 16, 1
	v_bfe_i32 v43, v114, 17, 1
	v_bfe_i32 v44, v114, 18, 1
	v_bfe_i32 v45, v114, 19, 1
	v_bfe_i32 v46, v114, 24, 1
	v_bfe_i32 v47, v114, 25, 1
	v_bfe_i32 v48, v114, 26, 1
	v_bfe_i32 v49, v114, 27, 1
	v_bfi_b32 v34, v34, v1, v232
	v_bfi_b32 v35, v35, v1, v232
	v_bfi_b32 v36, v36, v1, v232
	v_bfi_b32 v37, v37, v1, v232
	v_bfi_b32 v38, v38, v1, v232
	v_bfi_b32 v39, v39, v1, v232
	v_bfi_b32 v40, v40, v1, v232
	v_bfi_b32 v41, v41, v1, v232
	v_bfi_b32 v42, v42, v1, v232
	v_bfi_b32 v43, v43, v1, v232
	v_bfi_b32 v44, v44, v1, v232
	v_bfi_b32 v45, v45, v1, v232
	v_bfi_b32 v46, v46, v1, v232
	v_bfi_b32 v47, v47, v1, v232
	v_bfi_b32 v48, v48, v1, v232
	v_bfi_b32 v49, v49, v1, v232
	s_waitcnt lgkmcnt(4)
	s_nop 0
	v_mfma_f32_32x32x16_bf16 v[34:49], v[118:121], v[74:77], v[34:49]
	v_bfe_i32 v50, v116, 0, 1
	v_bfe_i32 v51, v116, 1, 1
	v_bfe_i32 v52, v116, 2, 1
	v_bfe_i32 v53, v116, 3, 1
	v_bfe_i32 v54, v116, 8, 1
	v_bfe_i32 v55, v116, 9, 1
	v_bfe_i32 v56, v116, 10, 1
	v_bfe_i32 v57, v116, 11, 1
	s_waitcnt lgkmcnt(4)
	v_mfma_f32_32x32x16_bf16 v[34:49], v[122:125], v[66:69], v[34:49]
	v_bfe_i32 v58, v116, 16, 1
	v_bfe_i32 v59, v116, 17, 1
	v_bfe_i32 v60, v116, 18, 1
	v_bfe_i32 v61, v116, 19, 1
	v_bfe_i32 v62, v116, 24, 1
	v_bfe_i32 v63, v116, 25, 1
	v_bfe_i32 v64, v116, 26, 1
	v_bfe_i32 v65, v116, 27, 1
	s_waitcnt lgkmcnt(4)
	v_mfma_f32_32x32x16_bf16 v[34:49], v[126:129], v[70:73], v[34:49]
	v_bfi_b32 v50, v50, v1, v232
	v_bfi_b32 v51, v51, v1, v232
	v_bfi_b32 v52, v52, v1, v232
	v_bfi_b32 v53, v53, v1, v232
	v_bfi_b32 v54, v54, v1, v232
	v_bfi_b32 v55, v55, v1, v232
	v_bfi_b32 v56, v56, v1, v232
	v_bfi_b32 v57, v57, v1, v232
	s_waitcnt lgkmcnt(0)
	v_mfma_f32_32x32x16_bf16 v[34:49], v[130:133], v[78:81], v[34:49]
	v_bfi_b32 v58, v58, v1, v232
	v_bfi_b32 v59, v59, v1, v232
	v_bfi_b32 v60, v60, v1, v232
	v_bfi_b32 v61, v61, v1, v232
	v_bfi_b32 v62, v62, v1, v232
	v_bfi_b32 v63, v63, v1, v232
	v_bfi_b32 v64, v64, v1, v232
	v_bfi_b32 v65, v65, v1, v232
	s_nop 1
	v_mfma_f32_32x32x16_bf16 v[50:65], v[182:185], v[74:77], v[50:65]
	ds_read_b64_tr_b16 v[198:199], v107 offset:27648
	ds_read_b64_tr_b16 v[200:201], v107 offset:28800
	ds_read_b64_tr_b16 v[202:203], v107 offset:29952
	ds_read_b64_tr_b16 v[204:205], v107 offset:31104
	v_mfma_f32_32x32x16_bf16 v[50:65], v[186:189], v[66:69], v[50:65]
	ds_read_b64_tr_b16 v[206:207], v107 offset:32256
	ds_read_b64_tr_b16 v[208:209], v107 offset:33408
	ds_read_b64_tr_b16 v[210:211], v107 offset:34560
	ds_read_b64_tr_b16 v[212:213], v107 offset:35712
	v_mfma_f32_32x32x16_bf16 v[50:65], v[190:193], v[70:73], v[50:65]
	ds_read_b64_tr_b16 v[214:215], v107 offset:27712
	ds_read_b64_tr_b16 v[216:217], v107 offset:28864
	ds_read_b64_tr_b16 v[218:219], v107 offset:30016
	ds_read_b64_tr_b16 v[220:221], v107 offset:31168
	v_mfma_f32_32x32x16_bf16 v[50:65], v[242:245], v[78:81], v[50:65]
	ds_read_b64_tr_b16 v[234:235], v107 offset:32320
	ds_read_b64_tr_b16 v[236:237], v107 offset:33472
	ds_read_b64_tr_b16 v[238:239], v107 offset:34624
	ds_read_b64_tr_b16 v[240:241], v107 offset:35776
	s_nop 1
	v_max3_f32 v108, v34, v35, v36
	v_max3_f32 v110, v37, v38, v39
	v_max3_f32 v114, v40, v41, v42
	v_max3_f32 v1, v43, v44, v45
	v_max3_f32 v108, v108, v46, v47
	v_max3_f32 v110, v110, v48, v49
	v_max3_f32 v114, v114, v50, v51
	v_max3_f32 v1, v1, v52, v53
	v_max3_f32 v108, v108, v54, v55
	v_max3_f32 v110, v110, v56, v57
	v_max3_f32 v114, v114, v58, v59
	v_max3_f32 v1, v1, v60, v61
	v_max3_f32 v108, v108, v62, v63
	v_max3_f32 v110, v110, v64, v65
	v_max3_f32 v1, v1, v114, s82
	v_max3_f32 v1, v1, v108, v110
	v_and_b32_e32 v110, 64, v224
	v_xor_b32_e32 v108, 32, v224
	v_add_u32_e32 v110, 64, v110
	v_cmp_lt_i32_e32 vcc, v108, v110
	s_nop 1
	v_cndmask_b32_e32 v108, v224, v108, vcc
	v_lshlrev_b32_e32 v108, 2, v108
	ds_bpermute_b32 v108, v108, v1
	s_waitcnt lgkmcnt(0)
	v_max_f32_e32 v108, v108, v108
	v_max_f32_e32 v1, v1, v108
	s_and_saveexec_b64 s[12:13], s[10:11]
	s_xor_b64 s[10:11], exec, s[12:13]
	s_cbranch_execnz .LBB0_940
	s_or_saveexec_b64 s[12:13], s[10:11]
	s_mov_b64 s[10:11], 0
	s_xor_b64 exec, exec, s[12:13]
	s_cbranch_execnz .LBB0_943
